# GLA prep phase: pair order remapped so that a workgroup's fifth pair is a (cheaper) context chunk
# baseline (speedup 1.0000x reference)
.LBB0_777:
	s_cmp_lt_i32 s90, 8
	s_cselect_b64 s[2:3], -1, 0
	s_add_u32 s36, s88, 0x115d000
	s_addc_u32 s37, s89, 0
	s_and_b64 s[18:19], s[2:3], s[0:1]
	s_andn2_b64 vcc, exec, s[18:19]
	s_cbranch_vccnz .LBB0_852
	s_cmpk_gt_i32 s58, 0x47f
	s_cbranch_scc1 .LBB0_851
	s_waitcnt vmcnt(0)
	v_readfirstlane_b32 s32, v0
	v_and_b32_e32 v2, 63, v0
	s_mov_b32 s33, 0xbfb8aa3b
	s_mov_b32 s35, 0x3f317217
	s_mov_b32 s36, 0xc1b8aa3b
	s_mov_b32 s37, 0xbd317217
	s_lshr_b32 s32, s32, 6
	v_lshlrev_b32_e32 v3, 3, v2
	v_lshlrev_b32_e32 v8, 1, v3
	v_lshlrev_b32_e32 v2, 2, v2
	s_lshl_b32 s92, s32, 10
	s_add_i32 s92, s92, 0x8000
	v_mov_b32_e32 v78, s92
	v_add_u32_e32 v9, s92, v8
	s_lshr_b32 s56, s58, 2
	s_lshr_b32 s92, s56, 5
	s_and_b32 s93, s56, 31
	s_add_i32 s93, s93, 4
	s_sub_i32 s94, s56, 0x100
	s_lshr_b32 s95, s94, 2
	s_and_b32 s94, s94, 3
	s_cmpk_lt_u32 s56, 0x100
	s_cselect_b32 s92, s92, s95
	s_cselect_b32 s93, s93, s94
	s_mul_i32 s34, s92, 144
	s_add_i32 s34, s34, s93
	s_and_b32 s57, s58, 3
	s_mul_i32 s57, s57, 36
	s_add_i32 s34, s34, s57
	s_mov_b32 s50, 0
	s_mul_hi_u32 s38, s34, 0x1c71c72
	s_mul_i32 s92, s38, 144
	s_sub_i32 s92, s34, s92
	s_mul_hi_u32 s40, s92, 0x71c71c8
	s_mul_i32 s93, s40, 36
	s_sub_i32 s39, s92, s93
	s_lshl_b32 s92, s38, 8
	s_lshl_b32 s93, s39, 6
	s_add_i32 s92, s92, s93
	s_addk_i32 s92, 0x4000
	s_lshl_b32 s94, s38, 11
	s_add_i32 s94, s94, s93
	s_addk_i32 s94, 0xff00
	s_cmp_lt_u32 s39, 4
	s_cselect_b32 s41, s92, s94
	s_lshl_b32 s92, s32, 3
	s_add_i32 s41, s41, s92
	s_lshl_b32 s95, s40, 8
	s_mul_i32 s92, s41, 0x1800
	s_add_u32 s92, s92, s95
	s_add_u32 s42, s96, s92
	s_addc_u32 s43, s97, 0
	s_lshl_b32 s92, s41, 10
	s_add_u32 s92, s92, s95
	s_add_u32 s44, s88, 0xa27d000
	s_addc_u32 s45, s89, 0
	s_add_u32 s44, s44, s92
	s_addc_u32 s45, s45, 0
	s_add_u32 s46, s44, 0x1000000
	s_addc_u32 s47, s45, 0
	s_lshl_b32 s92, s41, 7
	s_add_u32 s48, s88, 0xf1d000
	s_addc_u32 s49, s89, 0
	s_add_u32 s48, s48, s92
	s_addc_u32 s49, s49, 0
	s_lshl_b32 s95, s40, 9
	v_readlane_b32 s52, v251, 18
	v_readlane_b32 s53, v251, 19
	s_nop 3
	s_add_u32 s52, s52, s95
	s_addc_u32 s53, s53, 0
	global_load_dwordx2 v[10:11], v3, s[52:53]
	global_load_dwordx2 v[12:13], v3, s[52:53] offset:2048
	s_add_u32 s52, s52, 0x1000
	s_addc_u32 s53, s53, 0
	global_load_dwordx2 v[14:15], v3, s[52:53]
	global_load_dwordx2 v[16:17], v3, s[52:53] offset:2048
	s_add_u32 s52, s52, 0x1000
	s_addc_u32 s53, s53, 0
	global_load_dwordx2 v[18:19], v3, s[52:53]
	global_load_dwordx2 v[20:21], v3, s[52:53] offset:2048
	s_add_u32 s52, s52, 0x1000
	s_addc_u32 s53, s53, 0
	global_load_dwordx2 v[22:23], v3, s[52:53]
	global_load_dwordx2 v[24:25], v3, s[52:53] offset:2048
	s_add_u32 s52, s52, 0x1000
	s_addc_u32 s53, s53, 0
	global_load_dwordx2 v[26:27], v3, s[52:53]
	global_load_dwordx2 v[28:29], v3, s[52:53] offset:2048
	s_add_u32 s52, s52, 0x1000
	s_addc_u32 s53, s53, 0
	global_load_dwordx2 v[30:31], v3, s[52:53]
	global_load_dwordx2 v[32:33], v3, s[52:53] offset:2048
	s_add_u32 s52, s52, 0x1000
	s_addc_u32 s53, s53, 0
	global_load_dwordx2 v[34:35], v3, s[52:53]
	global_load_dwordx2 v[36:37], v3, s[52:53] offset:2048
	s_add_u32 s52, s52, 0x1000
	s_addc_u32 s53, s53, 0
	global_load_dwordx2 v[38:39], v3, s[52:53]
	global_load_dwordx2 v[40:41], v3, s[52:53] offset:2048
	v_readlane_b32 s52, v251, 24
	v_readlane_b32 s53, v251, 25
	s_nop 3
	s_add_u32 s52, s52, s95
	s_addc_u32 s53, s53, 0
	global_load_dwordx2 v[42:43], v3, s[52:53]
	global_load_dwordx2 v[44:45], v3, s[52:53] offset:2048
	s_add_u32 s52, s52, 0x1000
	s_addc_u32 s53, s53, 0
	global_load_dwordx2 v[46:47], v3, s[52:53]
	global_load_dwordx2 v[48:49], v3, s[52:53] offset:2048
	s_add_u32 s52, s52, 0x1000
	s_addc_u32 s53, s53, 0
	global_load_dwordx2 v[50:51], v3, s[52:53]
	global_load_dwordx2 v[52:53], v3, s[52:53] offset:2048
	s_add_u32 s52, s52, 0x1000
	s_addc_u32 s53, s53, 0
	global_load_dwordx2 v[54:55], v3, s[52:53]
	global_load_dwordx2 v[56:57], v3, s[52:53] offset:2048
	s_add_u32 s52, s52, 0x1000
	s_addc_u32 s53, s53, 0
	global_load_dwordx2 v[58:59], v3, s[52:53]
	global_load_dwordx2 v[60:61], v3, s[52:53] offset:2048
	s_add_u32 s52, s52, 0x1000
	s_addc_u32 s53, s53, 0
	global_load_dwordx2 v[62:63], v3, s[52:53]
	global_load_dwordx2 v[64:65], v3, s[52:53] offset:2048
	s_add_u32 s52, s52, 0x1000
	s_addc_u32 s53, s53, 0
	global_load_dwordx2 v[66:67], v3, s[52:53]
	global_load_dwordx2 v[68:69], v3, s[52:53] offset:2048
	s_add_u32 s52, s52, 0x1000
	s_addc_u32 s53, s53, 0
	global_load_dwordx2 v[70:71], v3, s[52:53]
	global_load_dwordx2 v[72:73], v3, s[52:53] offset:2048
	v_readlane_b32 s52, v251, 20
	v_readlane_b32 s53, v251, 21
	s_nop 3
	s_add_u32 s52, s52, s95
	s_addc_u32 s53, s53, 0
	global_load_dwordx2 v[74:75], v3, s[52:53]
	v_readlane_b32 s52, v251, 26
	v_readlane_b32 s53, v251, 27
	s_nop 3
	s_add_u32 s52, s52, s95
	s_addc_u32 s53, s53, 0
	global_load_dwordx2 v[76:77], v3, s[52:53]
	global_load_dwordx4 v[4:7], v8, s[48:49]
	s_mov_b64 s[52:53], s[42:43]
	global_load_dword v200, v2, s[52:53] offset:1024
	s_add_u32 s52, s52, 0x1800
	s_addc_u32 s53, s53, 0
	global_load_dword v201, v2, s[52:53] offset:1024
	s_add_u32 s52, s52, 0x1800
	s_addc_u32 s53, s53, 0
	global_load_dword v202, v2, s[52:53] offset:1024
	s_add_u32 s52, s52, 0x1800
	s_addc_u32 s53, s53, 0
	global_load_dword v203, v2, s[52:53] offset:1024
	s_add_u32 s52, s52, 0x1800
	s_addc_u32 s53, s53, 0
	global_load_dword v204, v2, s[52:53] offset:1024
	s_add_u32 s52, s52, 0x1800
	s_addc_u32 s53, s53, 0
	global_load_dword v205, v2, s[52:53] offset:1024
	s_add_u32 s52, s52, 0x1800
	s_addc_u32 s53, s53, 0
	global_load_dword v206, v2, s[52:53] offset:1024
	s_add_u32 s52, s52, 0x1800
	s_addc_u32 s53, s53, 0
	global_load_dword v207, v2, s[52:53] offset:1024
	s_cmp_lt_u32 s39, 4
	s_cbranch_scc1 .Lp7_noq_load_first
	s_mov_b64 s[52:53], s[42:43]
	global_load_dword v208, v2, s[52:53]
	s_add_u32 s52, s52, 0x1800
	s_addc_u32 s53, s53, 0
	global_load_dword v209, v2, s[52:53]
	s_add_u32 s52, s52, 0x1800
	s_addc_u32 s53, s53, 0
	global_load_dword v210, v2, s[52:53]
	s_add_u32 s52, s52, 0x1800
	s_addc_u32 s53, s53, 0
	global_load_dword v211, v2, s[52:53]
	s_add_u32 s52, s52, 0x1800
	s_addc_u32 s53, s53, 0
	global_load_dword v212, v2, s[52:53]
	s_add_u32 s52, s52, 0x1800
	s_addc_u32 s53, s53, 0
	global_load_dword v213, v2, s[52:53]
	s_add_u32 s52, s52, 0x1800
	s_addc_u32 s53, s53, 0
	global_load_dword v214, v2, s[52:53]
	s_add_u32 s52, s52, 0x1800
	s_addc_u32 s53, s53, 0
	global_load_dword v215, v2, s[52:53]

.Lp7_item:
	v_mov_b32_e32 v80, v200
	v_mov_b32_e32 v81, v201
	v_mov_b32_e32 v82, v202
	v_mov_b32_e32 v83, v203
	v_mov_b32_e32 v84, v204
	v_mov_b32_e32 v85, v205
	v_mov_b32_e32 v86, v206
	v_mov_b32_e32 v87, v207
	v_mov_b32_e32 v88, v208
	v_mov_b32_e32 v89, v209
	v_mov_b32_e32 v90, v210
	v_mov_b32_e32 v91, v211
	v_mov_b32_e32 v92, v212
	v_mov_b32_e32 v93, v213
	v_mov_b32_e32 v94, v214
	v_mov_b32_e32 v95, v215
	ds_write_b128 v9, v[4:7]
	ds_read_b128 v[216:219], v78 offset:0
	ds_read_b128 v[220:223], v78 offset:16
	ds_read_b128 v[224:227], v78 offset:32
	ds_read_b128 v[228:231], v78 offset:48
	ds_read_b128 v[232:235], v78 offset:64
	ds_read_b128 v[236:239], v78 offset:80
	ds_read_b128 v[240:243], v78 offset:96
	ds_read_b128 v[244:247], v78 offset:112
	s_waitcnt lgkmcnt(0)
	v_pk_fma_f32 v[128:129], v[10:11], v[216:217], v[74:75] op_sel_hi:[1,0,1]
	v_pk_fma_f32 v[128:129], v[12:13], v[216:217], v[128:129] op_sel:[0,1,0] op_sel_hi:[1,1,1]
	v_pk_fma_f32 v[128:129], v[14:15], v[218:219], v[128:129] op_sel_hi:[1,0,1]
	v_pk_fma_f32 v[128:129], v[16:17], v[218:219], v[128:129] op_sel:[0,1,0] op_sel_hi:[1,1,1]
	v_pk_fma_f32 v[128:129], v[18:19], v[220:221], v[128:129] op_sel_hi:[1,0,1]
	v_pk_fma_f32 v[128:129], v[20:21], v[220:221], v[128:129] op_sel:[0,1,0] op_sel_hi:[1,1,1]
	v_pk_fma_f32 v[128:129], v[22:23], v[222:223], v[128:129] op_sel_hi:[1,0,1]
	v_pk_fma_f32 v[128:129], v[24:25], v[222:223], v[128:129] op_sel:[0,1,0] op_sel_hi:[1,1,1]
	v_pk_fma_f32 v[128:129], v[26:27], v[224:225], v[128:129] op_sel_hi:[1,0,1]
	v_pk_fma_f32 v[128:129], v[28:29], v[224:225], v[128:129] op_sel:[0,1,0] op_sel_hi:[1,1,1]
	v_pk_fma_f32 v[128:129], v[30:31], v[226:227], v[128:129] op_sel_hi:[1,0,1]
	v_pk_fma_f32 v[128:129], v[32:33], v[226:227], v[128:129] op_sel:[0,1,0] op_sel_hi:[1,1,1]
	v_pk_fma_f32 v[128:129], v[34:35], v[228:229], v[128:129] op_sel_hi:[1,0,1]
	v_pk_fma_f32 v[128:129], v[36:37], v[228:229], v[128:129] op_sel:[0,1,0] op_sel_hi:[1,1,1]
	v_pk_fma_f32 v[128:129], v[38:39], v[230:231], v[128:129] op_sel_hi:[1,0,1]
	v_pk_fma_f32 v[128:129], v[40:41], v[230:231], v[128:129] op_sel:[0,1,0] op_sel_hi:[1,1,1]
	ds_read_b128 v[216:219], v78 offset:128
	ds_read_b128 v[220:223], v78 offset:144
	ds_read_b128 v[224:227], v78 offset:160
	ds_read_b128 v[228:231], v78 offset:176
	v_pk_fma_f32 v[130:131], v[42:43], v[232:233], v[76:77] op_sel_hi:[1,0,1]
	v_pk_fma_f32 v[130:131], v[44:45], v[232:233], v[130:131] op_sel:[0,1,0] op_sel_hi:[1,1,1]
	v_pk_fma_f32 v[130:131], v[46:47], v[234:235], v[130:131] op_sel_hi:[1,0,1]
	v_pk_fma_f32 v[130:131], v[48:49], v[234:235], v[130:131] op_sel:[0,1,0] op_sel_hi:[1,1,1]
	v_pk_fma_f32 v[130:131], v[50:51], v[236:237], v[130:131] op_sel_hi:[1,0,1]
	v_pk_fma_f32 v[130:131], v[52:53], v[236:237], v[130:131] op_sel:[0,1,0] op_sel_hi:[1,1,1]
	v_pk_fma_f32 v[130:131], v[54:55], v[238:239], v[130:131] op_sel_hi:[1,0,1]
	v_pk_fma_f32 v[130:131], v[56:57], v[238:239], v[130:131] op_sel:[0,1,0] op_sel_hi:[1,1,1]
	v_pk_fma_f32 v[130:131], v[58:59], v[240:241], v[130:131] op_sel_hi:[1,0,1]
	v_pk_fma_f32 v[130:131], v[60:61], v[240:241], v[130:131] op_sel:[0,1,0] op_sel_hi:[1,1,1]
	v_pk_fma_f32 v[130:131], v[62:63], v[242:243], v[130:131] op_sel_hi:[1,0,1]
	v_pk_fma_f32 v[130:131], v[64:65], v[242:243], v[130:131] op_sel:[0,1,0] op_sel_hi:[1,1,1]
	v_pk_fma_f32 v[130:131], v[66:67], v[244:245], v[130:131] op_sel_hi:[1,0,1]
	v_pk_fma_f32 v[130:131], v[68:69], v[244:245], v[130:131] op_sel:[0,1,0] op_sel_hi:[1,1,1]
	v_pk_fma_f32 v[130:131], v[70:71], v[246:247], v[130:131] op_sel_hi:[1,0,1]
	v_pk_fma_f32 v[130:131], v[72:73], v[246:247], v[130:131] op_sel:[0,1,0] op_sel_hi:[1,1,1]
	ds_read_b128 v[232:235], v78 offset:192
	ds_read_b128 v[236:239], v78 offset:208
	ds_read_b128 v[240:243], v78 offset:224
	ds_read_b128 v[244:247], v78 offset:240
	v_pk_mul_f32 v[132:133], v[128:129], s[36:37] op_sel_hi:[1,0]
	v_pk_mul_f32 v[134:135], v[130:131], s[36:37] op_sel_hi:[1,0]
	v_exp_f32_e64 v132, -|v132|
	v_exp_f32_e64 v133, -|v133|
	v_exp_f32_e64 v134, -|v134|
	v_exp_f32_e64 v135, -|v135|
	v_pk_add_f32 v[132:133], v[132:133], 1.0 op_sel_hi:[1,0]
	v_pk_add_f32 v[134:135], v[134:135], 1.0 op_sel_hi:[1,0]
	v_log_f32_e32 v136, v132
	v_log_f32_e32 v137, v133
	v_log_f32_e32 v138, v134
	v_log_f32_e32 v139, v135
	v_min_f32_e32 v128, 0, v128
	v_min_f32_e32 v129, 0, v129
	v_min_f32_e32 v130, 0, v130
	v_min_f32_e32 v131, 0, v131
	v_pk_fma_f32 v[96:97], v[136:137], s[36:37], v[128:129] op_sel:[0,1,0] op_sel_hi:[1,1,1]
	v_pk_fma_f32 v[112:113], v[138:139], s[36:37], v[130:131] op_sel:[0,1,0] op_sel_hi:[1,1,1]
	s_waitcnt lgkmcnt(0)
	v_pk_fma_f32 v[128:129], v[10:11], v[216:217], v[74:75] op_sel_hi:[1,0,1]
	v_pk_fma_f32 v[128:129], v[12:13], v[216:217], v[128:129] op_sel:[0,1,0] op_sel_hi:[1,1,1]
	v_pk_fma_f32 v[128:129], v[14:15], v[218:219], v[128:129] op_sel_hi:[1,0,1]
	v_pk_fma_f32 v[128:129], v[16:17], v[218:219], v[128:129] op_sel:[0,1,0] op_sel_hi:[1,1,1]
	v_pk_fma_f32 v[128:129], v[18:19], v[220:221], v[128:129] op_sel_hi:[1,0,1]
	v_pk_fma_f32 v[128:129], v[20:21], v[220:221], v[128:129] op_sel:[0,1,0] op_sel_hi:[1,1,1]
	v_pk_fma_f32 v[128:129], v[22:23], v[222:223], v[128:129] op_sel_hi:[1,0,1]
	v_pk_fma_f32 v[128:129], v[24:25], v[222:223], v[128:129] op_sel:[0,1,0] op_sel_hi:[1,1,1]
	v_pk_fma_f32 v[128:129], v[26:27], v[224:225], v[128:129] op_sel_hi:[1,0,1]
	v_pk_fma_f32 v[128:129], v[28:29], v[224:225], v[128:129] op_sel:[0,1,0] op_sel_hi:[1,1,1]
	v_pk_fma_f32 v[128:129], v[30:31], v[226:227], v[128:129] op_sel_hi:[1,0,1]
	v_pk_fma_f32 v[128:129], v[32:33], v[226:227], v[128:129] op_sel:[0,1,0] op_sel_hi:[1,1,1]
	v_pk_fma_f32 v[128:129], v[34:35], v[228:229], v[128:129] op_sel_hi:[1,0,1]
	v_pk_fma_f32 v[128:129], v[36:37], v[228:229], v[128:129] op_sel:[0,1,0] op_sel_hi:[1,1,1]
	v_pk_fma_f32 v[128:129], v[38:39], v[230:231], v[128:129] op_sel_hi:[1,0,1]
	v_pk_fma_f32 v[128:129], v[40:41], v[230:231], v[128:129] op_sel:[0,1,0] op_sel_hi:[1,1,1]
	ds_read_b128 v[216:219], v78 offset:256
	ds_read_b128 v[220:223], v78 offset:272
	ds_read_b128 v[224:227], v78 offset:288
	ds_read_b128 v[228:231], v78 offset:304
	v_pk_fma_f32 v[130:131], v[42:43], v[232:233], v[76:77] op_sel_hi:[1,0,1]
	v_pk_fma_f32 v[130:131], v[44:45], v[232:233], v[130:131] op_sel:[0,1,0] op_sel_hi:[1,1,1]
	v_pk_fma_f32 v[130:131], v[46:47], v[234:235], v[130:131] op_sel_hi:[1,0,1]
	v_pk_fma_f32 v[130:131], v[48:49], v[234:235], v[130:131] op_sel:[0,1,0] op_sel_hi:[1,1,1]
	v_pk_fma_f32 v[130:131], v[50:51], v[236:237], v[130:131] op_sel_hi:[1,0,1]
	v_pk_fma_f32 v[130:131], v[52:53], v[236:237], v[130:131] op_sel:[0,1,0] op_sel_hi:[1,1,1]
	v_pk_fma_f32 v[130:131], v[54:55], v[238:239], v[130:131] op_sel_hi:[1,0,1]
	v_pk_fma_f32 v[130:131], v[56:57], v[238:239], v[130:131] op_sel:[0,1,0] op_sel_hi:[1,1,1]
	v_pk_fma_f32 v[130:131], v[58:59], v[240:241], v[130:131] op_sel_hi:[1,0,1]
	v_pk_fma_f32 v[130:131], v[60:61], v[240:241], v[130:131] op_sel:[0,1,0] op_sel_hi:[1,1,1]
	v_pk_fma_f32 v[130:131], v[62:63], v[242:243], v[130:131] op_sel_hi:[1,0,1]
	v_pk_fma_f32 v[130:131], v[64:65], v[242:243], v[130:131] op_sel:[0,1,0] op_sel_hi:[1,1,1]
	v_pk_fma_f32 v[130:131], v[66:67], v[244:245], v[130:131] op_sel_hi:[1,0,1]
	v_pk_fma_f32 v[130:131], v[68:69], v[244:245], v[130:131] op_sel:[0,1,0] op_sel_hi:[1,1,1]
	v_pk_fma_f32 v[130:131], v[70:71], v[246:247], v[130:131] op_sel_hi:[1,0,1]
	v_pk_fma_f32 v[130:131], v[72:73], v[246:247], v[130:131] op_sel:[0,1,0] op_sel_hi:[1,1,1]
	ds_read_b128 v[232:235], v78 offset:320
	ds_read_b128 v[236:239], v78 offset:336
	ds_read_b128 v[240:243], v78 offset:352
	ds_read_b128 v[244:247], v78 offset:368
	v_pk_mul_f32 v[132:133], v[128:129], s[36:37] op_sel_hi:[1,0]
	v_pk_mul_f32 v[134:135], v[130:131], s[36:37] op_sel_hi:[1,0]
	v_exp_f32_e64 v132, -|v132|
	v_exp_f32_e64 v133, -|v133|
	v_exp_f32_e64 v134, -|v134|
	v_exp_f32_e64 v135, -|v135|
	v_pk_add_f32 v[132:133], v[132:133], 1.0 op_sel_hi:[1,0]
	v_pk_add_f32 v[134:135], v[134:135], 1.0 op_sel_hi:[1,0]
	v_log_f32_e32 v136, v132
	v_log_f32_e32 v137, v133
	v_log_f32_e32 v138, v134
	v_log_f32_e32 v139, v135
	v_min_f32_e32 v128, 0, v128
	v_min_f32_e32 v129, 0, v129
	v_min_f32_e32 v130, 0, v130
	v_min_f32_e32 v131, 0, v131
	v_pk_fma_f32 v[98:99], v[136:137], s[36:37], v[128:129] op_sel:[0,1,0] op_sel_hi:[1,1,1]
	v_pk_fma_f32 v[114:115], v[138:139], s[36:37], v[130:131] op_sel:[0,1,0] op_sel_hi:[1,1,1]
	s_waitcnt lgkmcnt(0)
	v_pk_fma_f32 v[128:129], v[10:11], v[216:217], v[74:75] op_sel_hi:[1,0,1]
	v_pk_fma_f32 v[128:129], v[12:13], v[216:217], v[128:129] op_sel:[0,1,0] op_sel_hi:[1,1,1]
	v_pk_fma_f32 v[128:129], v[14:15], v[218:219], v[128:129] op_sel_hi:[1,0,1]
	v_pk_fma_f32 v[128:129], v[16:17], v[218:219], v[128:129] op_sel:[0,1,0] op_sel_hi:[1,1,1]
	v_pk_fma_f32 v[128:129], v[18:19], v[220:221], v[128:129] op_sel_hi:[1,0,1]
	v_pk_fma_f32 v[128:129], v[20:21], v[220:221], v[128:129] op_sel:[0,1,0] op_sel_hi:[1,1,1]
	v_pk_fma_f32 v[128:129], v[22:23], v[222:223], v[128:129] op_sel_hi:[1,0,1]
	v_pk_fma_f32 v[128:129], v[24:25], v[222:223], v[128:129] op_sel:[0,1,0] op_sel_hi:[1,1,1]
	v_pk_fma_f32 v[128:129], v[26:27], v[224:225], v[128:129] op_sel_hi:[1,0,1]
	v_pk_fma_f32 v[128:129], v[28:29], v[224:225], v[128:129] op_sel:[0,1,0] op_sel_hi:[1,1,1]
	v_pk_fma_f32 v[128:129], v[30:31], v[226:227], v[128:129] op_sel_hi:[1,0,1]
	v_pk_fma_f32 v[128:129], v[32:33], v[226:227], v[128:129] op_sel:[0,1,0] op_sel_hi:[1,1,1]
	v_pk_fma_f32 v[128:129], v[34:35], v[228:229], v[128:129] op_sel_hi:[1,0,1]
	v_pk_fma_f32 v[128:129], v[36:37], v[228:229], v[128:129] op_sel:[0,1,0] op_sel_hi:[1,1,1]
	v_pk_fma_f32 v[128:129], v[38:39], v[230:231], v[128:129] op_sel_hi:[1,0,1]
	v_pk_fma_f32 v[128:129], v[40:41], v[230:231], v[128:129] op_sel:[0,1,0] op_sel_hi:[1,1,1]
	ds_read_b128 v[216:219], v78 offset:384
	ds_read_b128 v[220:223], v78 offset:400
	ds_read_b128 v[224:227], v78 offset:416
	ds_read_b128 v[228:231], v78 offset:432
	v_pk_fma_f32 v[130:131], v[42:43], v[232:233], v[76:77] op_sel_hi:[1,0,1]
	v_pk_fma_f32 v[130:131], v[44:45], v[232:233], v[130:131] op_sel:[0,1,0] op_sel_hi:[1,1,1]
	v_pk_fma_f32 v[130:131], v[46:47], v[234:235], v[130:131] op_sel_hi:[1,0,1]
	v_pk_fma_f32 v[130:131], v[48:49], v[234:235], v[130:131] op_sel:[0,1,0] op_sel_hi:[1,1,1]
	v_pk_fma_f32 v[130:131], v[50:51], v[236:237], v[130:131] op_sel_hi:[1,0,1]
	v_pk_fma_f32 v[130:131], v[52:53], v[236:237], v[130:131] op_sel:[0,1,0] op_sel_hi:[1,1,1]
	v_pk_fma_f32 v[130:131], v[54:55], v[238:239], v[130:131] op_sel_hi:[1,0,1]
	v_pk_fma_f32 v[130:131], v[56:57], v[238:239], v[130:131] op_sel:[0,1,0] op_sel_hi:[1,1,1]
	v_pk_fma_f32 v[130:131], v[58:59], v[240:241], v[130:131] op_sel_hi:[1,0,1]
	v_pk_fma_f32 v[130:131], v[60:61], v[240:241], v[130:131] op_sel:[0,1,0] op_sel_hi:[1,1,1]
	v_pk_fma_f32 v[130:131], v[62:63], v[242:243], v[130:131] op_sel_hi:[1,0,1]
	v_pk_fma_f32 v[130:131], v[64:65], v[242:243], v[130:131] op_sel:[0,1,0] op_sel_hi:[1,1,1]
	v_pk_fma_f32 v[130:131], v[66:67], v[244:245], v[130:131] op_sel_hi:[1,0,1]
	v_pk_fma_f32 v[130:131], v[68:69], v[244:245], v[130:131] op_sel:[0,1,0] op_sel_hi:[1,1,1]
	v_pk_fma_f32 v[130:131], v[70:71], v[246:247], v[130:131] op_sel_hi:[1,0,1]
	v_pk_fma_f32 v[130:131], v[72:73], v[246:247], v[130:131] op_sel:[0,1,0] op_sel_hi:[1,1,1]
	ds_read_b128 v[232:235], v78 offset:448
	ds_read_b128 v[236:239], v78 offset:464
	ds_read_b128 v[240:243], v78 offset:480
	ds_read_b128 v[244:247], v78 offset:496
	v_pk_mul_f32 v[132:133], v[128:129], s[36:37] op_sel_hi:[1,0]
	v_pk_mul_f32 v[134:135], v[130:131], s[36:37] op_sel_hi:[1,0]
	v_exp_f32_e64 v132, -|v132|
	v_exp_f32_e64 v133, -|v133|
	v_exp_f32_e64 v134, -|v134|
	v_exp_f32_e64 v135, -|v135|
	v_pk_add_f32 v[132:133], v[132:133], 1.0 op_sel_hi:[1,0]
	v_pk_add_f32 v[134:135], v[134:135], 1.0 op_sel_hi:[1,0]
	v_log_f32_e32 v136, v132
	v_log_f32_e32 v137, v133
	v_log_f32_e32 v138, v134
	v_log_f32_e32 v139, v135
	v_min_f32_e32 v128, 0, v128
	v_min_f32_e32 v129, 0, v129
	v_min_f32_e32 v130, 0, v130
	v_min_f32_e32 v131, 0, v131
	v_pk_fma_f32 v[100:101], v[136:137], s[36:37], v[128:129] op_sel:[0,1,0] op_sel_hi:[1,1,1]
	v_pk_fma_f32 v[116:117], v[138:139], s[36:37], v[130:131] op_sel:[0,1,0] op_sel_hi:[1,1,1]
	s_waitcnt lgkmcnt(0)
	v_pk_fma_f32 v[128:129], v[10:11], v[216:217], v[74:75] op_sel_hi:[1,0,1]
	v_pk_fma_f32 v[128:129], v[12:13], v[216:217], v[128:129] op_sel:[0,1,0] op_sel_hi:[1,1,1]
	v_pk_fma_f32 v[128:129], v[14:15], v[218:219], v[128:129] op_sel_hi:[1,0,1]
	v_pk_fma_f32 v[128:129], v[16:17], v[218:219], v[128:129] op_sel:[0,1,0] op_sel_hi:[1,1,1]
	v_pk_fma_f32 v[128:129], v[18:19], v[220:221], v[128:129] op_sel_hi:[1,0,1]
	v_pk_fma_f32 v[128:129], v[20:21], v[220:221], v[128:129] op_sel:[0,1,0] op_sel_hi:[1,1,1]
	v_pk_fma_f32 v[128:129], v[22:23], v[222:223], v[128:129] op_sel_hi:[1,0,1]
	v_pk_fma_f32 v[128:129], v[24:25], v[222:223], v[128:129] op_sel:[0,1,0] op_sel_hi:[1,1,1]
	v_pk_fma_f32 v[128:129], v[26:27], v[224:225], v[128:129] op_sel_hi:[1,0,1]
	v_pk_fma_f32 v[128:129], v[28:29], v[224:225], v[128:129] op_sel:[0,1,0] op_sel_hi:[1,1,1]
	v_pk_fma_f32 v[128:129], v[30:31], v[226:227], v[128:129] op_sel_hi:[1,0,1]
	v_pk_fma_f32 v[128:129], v[32:33], v[226:227], v[128:129] op_sel:[0,1,0] op_sel_hi:[1,1,1]
	v_pk_fma_f32 v[128:129], v[34:35], v[228:229], v[128:129] op_sel_hi:[1,0,1]
	v_pk_fma_f32 v[128:129], v[36:37], v[228:229], v[128:129] op_sel:[0,1,0] op_sel_hi:[1,1,1]
	v_pk_fma_f32 v[128:129], v[38:39], v[230:231], v[128:129] op_sel_hi:[1,0,1]
	v_pk_fma_f32 v[128:129], v[40:41], v[230:231], v[128:129] op_sel:[0,1,0] op_sel_hi:[1,1,1]
	ds_read_b128 v[216:219], v78 offset:512
	ds_read_b128 v[220:223], v78 offset:528
	ds_read_b128 v[224:227], v78 offset:544
	ds_read_b128 v[228:231], v78 offset:560
	v_pk_fma_f32 v[130:131], v[42:43], v[232:233], v[76:77] op_sel_hi:[1,0,1]
	v_pk_fma_f32 v[130:131], v[44:45], v[232:233], v[130:131] op_sel:[0,1,0] op_sel_hi:[1,1,1]
	v_pk_fma_f32 v[130:131], v[46:47], v[234:235], v[130:131] op_sel_hi:[1,0,1]
	v_pk_fma_f32 v[130:131], v[48:49], v[234:235], v[130:131] op_sel:[0,1,0] op_sel_hi:[1,1,1]
	v_pk_fma_f32 v[130:131], v[50:51], v[236:237], v[130:131] op_sel_hi:[1,0,1]
	v_pk_fma_f32 v[130:131], v[52:53], v[236:237], v[130:131] op_sel:[0,1,0] op_sel_hi:[1,1,1]
	v_pk_fma_f32 v[130:131], v[54:55], v[238:239], v[130:131] op_sel_hi:[1,0,1]
	v_pk_fma_f32 v[130:131], v[56:57], v[238:239], v[130:131] op_sel:[0,1,0] op_sel_hi:[1,1,1]
	v_pk_fma_f32 v[130:131], v[58:59], v[240:241], v[130:131] op_sel_hi:[1,0,1]
	v_pk_fma_f32 v[130:131], v[60:61], v[240:241], v[130:131] op_sel:[0,1,0] op_sel_hi:[1,1,1]
	v_pk_fma_f32 v[130:131], v[62:63], v[242:243], v[130:131] op_sel_hi:[1,0,1]
	v_pk_fma_f32 v[130:131], v[64:65], v[242:243], v[130:131] op_sel:[0,1,0] op_sel_hi:[1,1,1]
	v_pk_fma_f32 v[130:131], v[66:67], v[244:245], v[130:131] op_sel_hi:[1,0,1]
	v_pk_fma_f32 v[130:131], v[68:69], v[244:245], v[130:131] op_sel:[0,1,0] op_sel_hi:[1,1,1]
	v_pk_fma_f32 v[130:131], v[70:71], v[246:247], v[130:131] op_sel_hi:[1,0,1]
	v_pk_fma_f32 v[130:131], v[72:73], v[246:247], v[130:131] op_sel:[0,1,0] op_sel_hi:[1,1,1]
	ds_read_b128 v[232:235], v78 offset:576
	ds_read_b128 v[236:239], v78 offset:592
	ds_read_b128 v[240:243], v78 offset:608
	ds_read_b128 v[244:247], v78 offset:624
	v_pk_mul_f32 v[132:133], v[128:129], s[36:37] op_sel_hi:[1,0]
	v_pk_mul_f32 v[134:135], v[130:131], s[36:37] op_sel_hi:[1,0]
	v_exp_f32_e64 v132, -|v132|
	v_exp_f32_e64 v133, -|v133|
	v_exp_f32_e64 v134, -|v134|
	v_exp_f32_e64 v135, -|v135|
	v_pk_add_f32 v[132:133], v[132:133], 1.0 op_sel_hi:[1,0]
	v_pk_add_f32 v[134:135], v[134:135], 1.0 op_sel_hi:[1,0]
	v_log_f32_e32 v136, v132
	v_log_f32_e32 v137, v133
	v_log_f32_e32 v138, v134
	v_log_f32_e32 v139, v135
	v_min_f32_e32 v128, 0, v128
	v_min_f32_e32 v129, 0, v129
	v_min_f32_e32 v130, 0, v130
	v_min_f32_e32 v131, 0, v131
	v_pk_fma_f32 v[102:103], v[136:137], s[36:37], v[128:129] op_sel:[0,1,0] op_sel_hi:[1,1,1]
	v_pk_fma_f32 v[118:119], v[138:139], s[36:37], v[130:131] op_sel:[0,1,0] op_sel_hi:[1,1,1]
	s_waitcnt lgkmcnt(0)
	v_pk_fma_f32 v[128:129], v[10:11], v[216:217], v[74:75] op_sel_hi:[1,0,1]
	v_pk_fma_f32 v[128:129], v[12:13], v[216:217], v[128:129] op_sel:[0,1,0] op_sel_hi:[1,1,1]
	v_pk_fma_f32 v[128:129], v[14:15], v[218:219], v[128:129] op_sel_hi:[1,0,1]
	v_pk_fma_f32 v[128:129], v[16:17], v[218:219], v[128:129] op_sel:[0,1,0] op_sel_hi:[1,1,1]
	v_pk_fma_f32 v[128:129], v[18:19], v[220:221], v[128:129] op_sel_hi:[1,0,1]
	v_pk_fma_f32 v[128:129], v[20:21], v[220:221], v[128:129] op_sel:[0,1,0] op_sel_hi:[1,1,1]
	v_pk_fma_f32 v[128:129], v[22:23], v[222:223], v[128:129] op_sel_hi:[1,0,1]
	v_pk_fma_f32 v[128:129], v[24:25], v[222:223], v[128:129] op_sel:[0,1,0] op_sel_hi:[1,1,1]
	v_pk_fma_f32 v[128:129], v[26:27], v[224:225], v[128:129] op_sel_hi:[1,0,1]
	v_pk_fma_f32 v[128:129], v[28:29], v[224:225], v[128:129] op_sel:[0,1,0] op_sel_hi:[1,1,1]
	v_pk_fma_f32 v[128:129], v[30:31], v[226:227], v[128:129] op_sel_hi:[1,0,1]
	v_pk_fma_f32 v[128:129], v[32:33], v[226:227], v[128:129] op_sel:[0,1,0] op_sel_hi:[1,1,1]
	v_pk_fma_f32 v[128:129], v[34:35], v[228:229], v[128:129] op_sel_hi:[1,0,1]
	v_pk_fma_f32 v[128:129], v[36:37], v[228:229], v[128:129] op_sel:[0,1,0] op_sel_hi:[1,1,1]
	v_pk_fma_f32 v[128:129], v[38:39], v[230:231], v[128:129] op_sel_hi:[1,0,1]
	v_pk_fma_f32 v[128:129], v[40:41], v[230:231], v[128:129] op_sel:[0,1,0] op_sel_hi:[1,1,1]
	ds_read_b128 v[216:219], v78 offset:640
	ds_read_b128 v[220:223], v78 offset:656
	ds_read_b128 v[224:227], v78 offset:672
	ds_read_b128 v[228:231], v78 offset:688
	v_pk_fma_f32 v[130:131], v[42:43], v[232:233], v[76:77] op_sel_hi:[1,0,1]
	v_pk_fma_f32 v[130:131], v[44:45], v[232:233], v[130:131] op_sel:[0,1,0] op_sel_hi:[1,1,1]
	v_pk_fma_f32 v[130:131], v[46:47], v[234:235], v[130:131] op_sel_hi:[1,0,1]
	v_pk_fma_f32 v[130:131], v[48:49], v[234:235], v[130:131] op_sel:[0,1,0] op_sel_hi:[1,1,1]
	v_pk_fma_f32 v[130:131], v[50:51], v[236:237], v[130:131] op_sel_hi:[1,0,1]
	v_pk_fma_f32 v[130:131], v[52:53], v[236:237], v[130:131] op_sel:[0,1,0] op_sel_hi:[1,1,1]
	v_pk_fma_f32 v[130:131], v[54:55], v[238:239], v[130:131] op_sel_hi:[1,0,1]
	v_pk_fma_f32 v[130:131], v[56:57], v[238:239], v[130:131] op_sel:[0,1,0] op_sel_hi:[1,1,1]
	v_pk_fma_f32 v[130:131], v[58:59], v[240:241], v[130:131] op_sel_hi:[1,0,1]
	v_pk_fma_f32 v[130:131], v[60:61], v[240:241], v[130:131] op_sel:[0,1,0] op_sel_hi:[1,1,1]
	v_pk_fma_f32 v[130:131], v[62:63], v[242:243], v[130:131] op_sel_hi:[1,0,1]
	v_pk_fma_f32 v[130:131], v[64:65], v[242:243], v[130:131] op_sel:[0,1,0] op_sel_hi:[1,1,1]
	v_pk_fma_f32 v[130:131], v[66:67], v[244:245], v[130:131] op_sel_hi:[1,0,1]
	v_pk_fma_f32 v[130:131], v[68:69], v[244:245], v[130:131] op_sel:[0,1,0] op_sel_hi:[1,1,1]
	v_pk_fma_f32 v[130:131], v[70:71], v[246:247], v[130:131] op_sel_hi:[1,0,1]
	v_pk_fma_f32 v[130:131], v[72:73], v[246:247], v[130:131] op_sel:[0,1,0] op_sel_hi:[1,1,1]
	ds_read_b128 v[232:235], v78 offset:704
	ds_read_b128 v[236:239], v78 offset:720
	ds_read_b128 v[240:243], v78 offset:736
	ds_read_b128 v[244:247], v78 offset:752
	v_pk_mul_f32 v[132:133], v[128:129], s[36:37] op_sel_hi:[1,0]
	v_pk_mul_f32 v[134:135], v[130:131], s[36:37] op_sel_hi:[1,0]
	v_exp_f32_e64 v132, -|v132|
	v_exp_f32_e64 v133, -|v133|
	v_exp_f32_e64 v134, -|v134|
	v_exp_f32_e64 v135, -|v135|
	v_pk_add_f32 v[132:133], v[132:133], 1.0 op_sel_hi:[1,0]
	v_pk_add_f32 v[134:135], v[134:135], 1.0 op_sel_hi:[1,0]
	v_log_f32_e32 v136, v132
	v_log_f32_e32 v137, v133
	v_log_f32_e32 v138, v134
	v_log_f32_e32 v139, v135
	v_min_f32_e32 v128, 0, v128
	v_min_f32_e32 v129, 0, v129
	v_min_f32_e32 v130, 0, v130
	v_min_f32_e32 v131, 0, v131
	v_pk_fma_f32 v[104:105], v[136:137], s[36:37], v[128:129] op_sel:[0,1,0] op_sel_hi:[1,1,1]
	v_pk_fma_f32 v[120:121], v[138:139], s[36:37], v[130:131] op_sel:[0,1,0] op_sel_hi:[1,1,1]
	s_waitcnt lgkmcnt(0)
	v_pk_fma_f32 v[128:129], v[10:11], v[216:217], v[74:75] op_sel_hi:[1,0,1]
	v_pk_fma_f32 v[128:129], v[12:13], v[216:217], v[128:129] op_sel:[0,1,0] op_sel_hi:[1,1,1]
	v_pk_fma_f32 v[128:129], v[14:15], v[218:219], v[128:129] op_sel_hi:[1,0,1]
	v_pk_fma_f32 v[128:129], v[16:17], v[218:219], v[128:129] op_sel:[0,1,0] op_sel_hi:[1,1,1]
	v_pk_fma_f32 v[128:129], v[18:19], v[220:221], v[128:129] op_sel_hi:[1,0,1]
	v_pk_fma_f32 v[128:129], v[20:21], v[220:221], v[128:129] op_sel:[0,1,0] op_sel_hi:[1,1,1]
	v_pk_fma_f32 v[128:129], v[22:23], v[222:223], v[128:129] op_sel_hi:[1,0,1]
	v_pk_fma_f32 v[128:129], v[24:25], v[222:223], v[128:129] op_sel:[0,1,0] op_sel_hi:[1,1,1]
	v_pk_fma_f32 v[128:129], v[26:27], v[224:225], v[128:129] op_sel_hi:[1,0,1]
	v_pk_fma_f32 v[128:129], v[28:29], v[224:225], v[128:129] op_sel:[0,1,0] op_sel_hi:[1,1,1]
	v_pk_fma_f32 v[128:129], v[30:31], v[226:227], v[128:129] op_sel_hi:[1,0,1]
	v_pk_fma_f32 v[128:129], v[32:33], v[226:227], v[128:129] op_sel:[0,1,0] op_sel_hi:[1,1,1]
	v_pk_fma_f32 v[128:129], v[34:35], v[228:229], v[128:129] op_sel_hi:[1,0,1]
	v_pk_fma_f32 v[128:129], v[36:37], v[228:229], v[128:129] op_sel:[0,1,0] op_sel_hi:[1,1,1]
	v_pk_fma_f32 v[128:129], v[38:39], v[230:231], v[128:129] op_sel_hi:[1,0,1]
	v_pk_fma_f32 v[128:129], v[40:41], v[230:231], v[128:129] op_sel:[0,1,0] op_sel_hi:[1,1,1]
	ds_read_b128 v[216:219], v78 offset:768
	ds_read_b128 v[220:223], v78 offset:784
	ds_read_b128 v[224:227], v78 offset:800
	ds_read_b128 v[228:231], v78 offset:816
	v_pk_fma_f32 v[130:131], v[42:43], v[232:233], v[76:77] op_sel_hi:[1,0,1]
	v_pk_fma_f32 v[130:131], v[44:45], v[232:233], v[130:131] op_sel:[0,1,0] op_sel_hi:[1,1,1]
	v_pk_fma_f32 v[130:131], v[46:47], v[234:235], v[130:131] op_sel_hi:[1,0,1]
	v_pk_fma_f32 v[130:131], v[48:49], v[234:235], v[130:131] op_sel:[0,1,0] op_sel_hi:[1,1,1]
	v_pk_fma_f32 v[130:131], v[50:51], v[236:237], v[130:131] op_sel_hi:[1,0,1]
	v_pk_fma_f32 v[130:131], v[52:53], v[236:237], v[130:131] op_sel:[0,1,0] op_sel_hi:[1,1,1]
	v_pk_fma_f32 v[130:131], v[54:55], v[238:239], v[130:131] op_sel_hi:[1,0,1]
	v_pk_fma_f32 v[130:131], v[56:57], v[238:239], v[130:131] op_sel:[0,1,0] op_sel_hi:[1,1,1]
	v_pk_fma_f32 v[130:131], v[58:59], v[240:241], v[130:131] op_sel_hi:[1,0,1]
	v_pk_fma_f32 v[130:131], v[60:61], v[240:241], v[130:131] op_sel:[0,1,0] op_sel_hi:[1,1,1]
	v_pk_fma_f32 v[130:131], v[62:63], v[242:243], v[130:131] op_sel_hi:[1,0,1]
	v_pk_fma_f32 v[130:131], v[64:65], v[242:243], v[130:131] op_sel:[0,1,0] op_sel_hi:[1,1,1]
	v_pk_fma_f32 v[130:131], v[66:67], v[244:245], v[130:131] op_sel_hi:[1,0,1]
	v_pk_fma_f32 v[130:131], v[68:69], v[244:245], v[130:131] op_sel:[0,1,0] op_sel_hi:[1,1,1]
	v_pk_fma_f32 v[130:131], v[70:71], v[246:247], v[130:131] op_sel_hi:[1,0,1]
	v_pk_fma_f32 v[130:131], v[72:73], v[246:247], v[130:131] op_sel:[0,1,0] op_sel_hi:[1,1,1]
	ds_read_b128 v[232:235], v78 offset:832
	ds_read_b128 v[236:239], v78 offset:848
	ds_read_b128 v[240:243], v78 offset:864
	ds_read_b128 v[244:247], v78 offset:880
	v_pk_mul_f32 v[132:133], v[128:129], s[36:37] op_sel_hi:[1,0]
	v_pk_mul_f32 v[134:135], v[130:131], s[36:37] op_sel_hi:[1,0]
	v_exp_f32_e64 v132, -|v132|
	v_exp_f32_e64 v133, -|v133|
	v_exp_f32_e64 v134, -|v134|
	v_exp_f32_e64 v135, -|v135|
	v_pk_add_f32 v[132:133], v[132:133], 1.0 op_sel_hi:[1,0]
	v_pk_add_f32 v[134:135], v[134:135], 1.0 op_sel_hi:[1,0]
	v_log_f32_e32 v136, v132
	v_log_f32_e32 v137, v133
	v_log_f32_e32 v138, v134
	v_log_f32_e32 v139, v135
	v_min_f32_e32 v128, 0, v128
	v_min_f32_e32 v129, 0, v129
	v_min_f32_e32 v130, 0, v130
	v_min_f32_e32 v131, 0, v131
	v_pk_fma_f32 v[106:107], v[136:137], s[36:37], v[128:129] op_sel:[0,1,0] op_sel_hi:[1,1,1]
	v_pk_fma_f32 v[122:123], v[138:139], s[36:37], v[130:131] op_sel:[0,1,0] op_sel_hi:[1,1,1]
	s_waitcnt lgkmcnt(0)
	v_pk_fma_f32 v[128:129], v[10:11], v[216:217], v[74:75] op_sel_hi:[1,0,1]
	v_pk_fma_f32 v[128:129], v[12:13], v[216:217], v[128:129] op_sel:[0,1,0] op_sel_hi:[1,1,1]
	v_pk_fma_f32 v[128:129], v[14:15], v[218:219], v[128:129] op_sel_hi:[1,0,1]
	v_pk_fma_f32 v[128:129], v[16:17], v[218:219], v[128:129] op_sel:[0,1,0] op_sel_hi:[1,1,1]
	v_pk_fma_f32 v[128:129], v[18:19], v[220:221], v[128:129] op_sel_hi:[1,0,1]
	v_pk_fma_f32 v[128:129], v[20:21], v[220:221], v[128:129] op_sel:[0,1,0] op_sel_hi:[1,1,1]
	v_pk_fma_f32 v[128:129], v[22:23], v[222:223], v[128:129] op_sel_hi:[1,0,1]
	v_pk_fma_f32 v[128:129], v[24:25], v[222:223], v[128:129] op_sel:[0,1,0] op_sel_hi:[1,1,1]
	v_pk_fma_f32 v[128:129], v[26:27], v[224:225], v[128:129] op_sel_hi:[1,0,1]
	v_pk_fma_f32 v[128:129], v[28:29], v[224:225], v[128:129] op_sel:[0,1,0] op_sel_hi:[1,1,1]
	v_pk_fma_f32 v[128:129], v[30:31], v[226:227], v[128:129] op_sel_hi:[1,0,1]
	v_pk_fma_f32 v[128:129], v[32:33], v[226:227], v[128:129] op_sel:[0,1,0] op_sel_hi:[1,1,1]
	v_pk_fma_f32 v[128:129], v[34:35], v[228:229], v[128:129] op_sel_hi:[1,0,1]
	v_pk_fma_f32 v[128:129], v[36:37], v[228:229], v[128:129] op_sel:[0,1,0] op_sel_hi:[1,1,1]
	v_pk_fma_f32 v[128:129], v[38:39], v[230:231], v[128:129] op_sel_hi:[1,0,1]
	v_pk_fma_f32 v[128:129], v[40:41], v[230:231], v[128:129] op_sel:[0,1,0] op_sel_hi:[1,1,1]
	ds_read_b128 v[216:219], v78 offset:896
	ds_read_b128 v[220:223], v78 offset:912
	ds_read_b128 v[224:227], v78 offset:928
	ds_read_b128 v[228:231], v78 offset:944
	v_pk_fma_f32 v[130:131], v[42:43], v[232:233], v[76:77] op_sel_hi:[1,0,1]
	v_pk_fma_f32 v[130:131], v[44:45], v[232:233], v[130:131] op_sel:[0,1,0] op_sel_hi:[1,1,1]
	v_pk_fma_f32 v[130:131], v[46:47], v[234:235], v[130:131] op_sel_hi:[1,0,1]
	v_pk_fma_f32 v[130:131], v[48:49], v[234:235], v[130:131] op_sel:[0,1,0] op_sel_hi:[1,1,1]
	v_pk_fma_f32 v[130:131], v[50:51], v[236:237], v[130:131] op_sel_hi:[1,0,1]
	v_pk_fma_f32 v[130:131], v[52:53], v[236:237], v[130:131] op_sel:[0,1,0] op_sel_hi:[1,1,1]
	v_pk_fma_f32 v[130:131], v[54:55], v[238:239], v[130:131] op_sel_hi:[1,0,1]
	v_pk_fma_f32 v[130:131], v[56:57], v[238:239], v[130:131] op_sel:[0,1,0] op_sel_hi:[1,1,1]
	v_pk_fma_f32 v[130:131], v[58:59], v[240:241], v[130:131] op_sel_hi:[1,0,1]
	v_pk_fma_f32 v[130:131], v[60:61], v[240:241], v[130:131] op_sel:[0,1,0] op_sel_hi:[1,1,1]
	v_pk_fma_f32 v[130:131], v[62:63], v[242:243], v[130:131] op_sel_hi:[1,0,1]
	v_pk_fma_f32 v[130:131], v[64:65], v[242:243], v[130:131] op_sel:[0,1,0] op_sel_hi:[1,1,1]
	v_pk_fma_f32 v[130:131], v[66:67], v[244:245], v[130:131] op_sel_hi:[1,0,1]
	v_pk_fma_f32 v[130:131], v[68:69], v[244:245], v[130:131] op_sel:[0,1,0] op_sel_hi:[1,1,1]
	v_pk_fma_f32 v[130:131], v[70:71], v[246:247], v[130:131] op_sel_hi:[1,0,1]
	v_pk_fma_f32 v[130:131], v[72:73], v[246:247], v[130:131] op_sel:[0,1,0] op_sel_hi:[1,1,1]
	ds_read_b128 v[232:235], v78 offset:960
	ds_read_b128 v[236:239], v78 offset:976
	ds_read_b128 v[240:243], v78 offset:992
	ds_read_b128 v[244:247], v78 offset:1008
	v_pk_mul_f32 v[132:133], v[128:129], s[36:37] op_sel_hi:[1,0]
	v_pk_mul_f32 v[134:135], v[130:131], s[36:37] op_sel_hi:[1,0]
	v_exp_f32_e64 v132, -|v132|
	v_exp_f32_e64 v133, -|v133|
	v_exp_f32_e64 v134, -|v134|
	v_exp_f32_e64 v135, -|v135|
	v_pk_add_f32 v[132:133], v[132:133], 1.0 op_sel_hi:[1,0]
	v_pk_add_f32 v[134:135], v[134:135], 1.0 op_sel_hi:[1,0]
	v_log_f32_e32 v136, v132
	v_log_f32_e32 v137, v133
	v_log_f32_e32 v138, v134
	v_log_f32_e32 v139, v135
	v_min_f32_e32 v128, 0, v128
	v_min_f32_e32 v129, 0, v129
	v_min_f32_e32 v130, 0, v130
	v_min_f32_e32 v131, 0, v131
	v_pk_fma_f32 v[108:109], v[136:137], s[36:37], v[128:129] op_sel:[0,1,0] op_sel_hi:[1,1,1]
	v_pk_fma_f32 v[124:125], v[138:139], s[36:37], v[130:131] op_sel:[0,1,0] op_sel_hi:[1,1,1]
	s_waitcnt lgkmcnt(0)
	v_pk_fma_f32 v[128:129], v[10:11], v[216:217], v[74:75] op_sel_hi:[1,0,1]
	v_pk_fma_f32 v[128:129], v[12:13], v[216:217], v[128:129] op_sel:[0,1,0] op_sel_hi:[1,1,1]
	v_pk_fma_f32 v[128:129], v[14:15], v[218:219], v[128:129] op_sel_hi:[1,0,1]
	v_pk_fma_f32 v[128:129], v[16:17], v[218:219], v[128:129] op_sel:[0,1,0] op_sel_hi:[1,1,1]
	v_pk_fma_f32 v[128:129], v[18:19], v[220:221], v[128:129] op_sel_hi:[1,0,1]
	v_pk_fma_f32 v[128:129], v[20:21], v[220:221], v[128:129] op_sel:[0,1,0] op_sel_hi:[1,1,1]
	v_pk_fma_f32 v[128:129], v[22:23], v[222:223], v[128:129] op_sel_hi:[1,0,1]
	v_pk_fma_f32 v[128:129], v[24:25], v[222:223], v[128:129] op_sel:[0,1,0] op_sel_hi:[1,1,1]
	v_pk_fma_f32 v[128:129], v[26:27], v[224:225], v[128:129] op_sel_hi:[1,0,1]
	v_pk_fma_f32 v[128:129], v[28:29], v[224:225], v[128:129] op_sel:[0,1,0] op_sel_hi:[1,1,1]
	v_pk_fma_f32 v[128:129], v[30:31], v[226:227], v[128:129] op_sel_hi:[1,0,1]
	v_pk_fma_f32 v[128:129], v[32:33], v[226:227], v[128:129] op_sel:[0,1,0] op_sel_hi:[1,1,1]
	v_pk_fma_f32 v[128:129], v[34:35], v[228:229], v[128:129] op_sel_hi:[1,0,1]
	v_pk_fma_f32 v[128:129], v[36:37], v[228:229], v[128:129] op_sel:[0,1,0] op_sel_hi:[1,1,1]
	v_pk_fma_f32 v[128:129], v[38:39], v[230:231], v[128:129] op_sel_hi:[1,0,1]
	v_pk_fma_f32 v[128:129], v[40:41], v[230:231], v[128:129] op_sel:[0,1,0] op_sel_hi:[1,1,1]
	v_pk_fma_f32 v[130:131], v[42:43], v[232:233], v[76:77] op_sel_hi:[1,0,1]
	v_pk_fma_f32 v[130:131], v[44:45], v[232:233], v[130:131] op_sel:[0,1,0] op_sel_hi:[1,1,1]
	v_pk_fma_f32 v[130:131], v[46:47], v[234:235], v[130:131] op_sel_hi:[1,0,1]
	v_pk_fma_f32 v[130:131], v[48:49], v[234:235], v[130:131] op_sel:[0,1,0] op_sel_hi:[1,1,1]
	v_pk_fma_f32 v[130:131], v[50:51], v[236:237], v[130:131] op_sel_hi:[1,0,1]
	v_pk_fma_f32 v[130:131], v[52:53], v[236:237], v[130:131] op_sel:[0,1,0] op_sel_hi:[1,1,1]
	v_pk_fma_f32 v[130:131], v[54:55], v[238:239], v[130:131] op_sel_hi:[1,0,1]
	v_pk_fma_f32 v[130:131], v[56:57], v[238:239], v[130:131] op_sel:[0,1,0] op_sel_hi:[1,1,1]
	v_pk_fma_f32 v[130:131], v[58:59], v[240:241], v[130:131] op_sel_hi:[1,0,1]
	v_pk_fma_f32 v[130:131], v[60:61], v[240:241], v[130:131] op_sel:[0,1,0] op_sel_hi:[1,1,1]
	v_pk_fma_f32 v[130:131], v[62:63], v[242:243], v[130:131] op_sel_hi:[1,0,1]
	v_pk_fma_f32 v[130:131], v[64:65], v[242:243], v[130:131] op_sel:[0,1,0] op_sel_hi:[1,1,1]
	v_pk_fma_f32 v[130:131], v[66:67], v[244:245], v[130:131] op_sel_hi:[1,0,1]
	v_pk_fma_f32 v[130:131], v[68:69], v[244:245], v[130:131] op_sel:[0,1,0] op_sel_hi:[1,1,1]
	v_pk_fma_f32 v[130:131], v[70:71], v[246:247], v[130:131] op_sel_hi:[1,0,1]
	v_pk_fma_f32 v[130:131], v[72:73], v[246:247], v[130:131] op_sel:[0,1,0] op_sel_hi:[1,1,1]
	v_pk_mul_f32 v[132:133], v[128:129], s[36:37] op_sel_hi:[1,0]
	v_pk_mul_f32 v[134:135], v[130:131], s[36:37] op_sel_hi:[1,0]
	v_exp_f32_e64 v132, -|v132|
	v_exp_f32_e64 v133, -|v133|
	v_exp_f32_e64 v134, -|v134|
	v_exp_f32_e64 v135, -|v135|
	v_pk_add_f32 v[132:133], v[132:133], 1.0 op_sel_hi:[1,0]
	v_pk_add_f32 v[134:135], v[134:135], 1.0 op_sel_hi:[1,0]
	v_log_f32_e32 v136, v132
	v_log_f32_e32 v137, v133
	v_log_f32_e32 v138, v134
	v_log_f32_e32 v139, v135
	v_min_f32_e32 v128, 0, v128
	v_min_f32_e32 v129, 0, v129
	v_min_f32_e32 v130, 0, v130
	v_min_f32_e32 v131, 0, v131
	v_pk_fma_f32 v[110:111], v[136:137], s[36:37], v[128:129] op_sel:[0,1,0] op_sel_hi:[1,1,1]
	v_pk_fma_f32 v[126:127], v[138:139], s[36:37], v[130:131] op_sel:[0,1,0] op_sel_hi:[1,1,1]
	v_readlane_b32 s69, v251, 49
	s_nop 3
	s_add_i32 s56, s56, 64
	s_movk_i32 s51, 0x480
	s_cmpk_lt_i32 s56, 0x120
	s_cbranch_scc0 .Lp7_jdone
	s_lshr_b32 s92, s56, 5
	s_and_b32 s93, s56, 31
	s_add_i32 s93, s93, 4
	s_sub_i32 s94, s56, 0x100
	s_lshr_b32 s95, s94, 2
	s_and_b32 s94, s94, 3
	s_cmpk_lt_u32 s56, 0x100
	s_cselect_b32 s92, s92, s95
	s_cselect_b32 s93, s93, s94
	s_mul_i32 s51, s92, 144
	s_add_i32 s51, s51, s93
	s_and_b32 s57, s58, 3
	s_mul_i32 s57, s57, 36
	s_add_i32 s51, s51, s57
